# XCD barrier polls with 3 staggered loads in flight (lower release-detection latency); on top of v063
# speedup vs baseline: 1.0052x; 1.0036x over previous
; __device__ __forceinline__ unsigned xb_ld(unsigned* p)              { return __hip_atomic_load(p, __ATOMIC_RELAXED, __HIP_MEMORY_SCOPE_AGENT); }
; #define XB_SPIN(cond, bar) do { unsigned _sp = 0; while (cond) { __builtin_amdgcn_s_sleep(1); \
;     if ((++_sp & 255u) == 0u) { if (xb_ld(&(bar)[XB_TMO])) break; if (_sp > XB_SPIN_CAP) { atomicAdd(&(bar)[XB_TMO], 1u); break; } } } } while (0)
; __device__ __forceinline__ void xcd_barrier(unsigned* bar, volatile LAS unsigned* st, bool is_t0) {
;     ...
;             XB_SPIN(xb_ld(&bar[XB_XGEN(x)]) == gen, bar);
.Lfb0_poll:
	s_mov_b32 s98, 0x20000
	global_load_dword v250, v253, s[96:97] sc1
	s_sleep 12
	global_load_dword v251, v253, s[96:97] sc1
	s_sleep 12
	global_load_dword v252, v253, s[96:97] sc1
.Lfb0_spin:
	s_waitcnt vmcnt(2)
	v_readfirstlane_b32 s91, v250
	s_cmp_ge_u32 s91, s99
	s_cbranch_scc1 .Lfb0_done
	global_load_dword v250, v253, s[96:97] sc1
	s_waitcnt vmcnt(2)
	v_readfirstlane_b32 s91, v251
	s_cmp_ge_u32 s91, s99
	s_cbranch_scc1 .Lfb0_done
	global_load_dword v251, v253, s[96:97] sc1
	s_waitcnt vmcnt(2)
	v_readfirstlane_b32 s91, v252
	s_cmp_ge_u32 s91, s99
	s_cbranch_scc1 .Lfb0_done
	global_load_dword v252, v253, s[96:97] sc1
	s_sub_i32 s98, s98, 1
	s_cmp_lg_u32 s98, 0
	s_cbranch_scc1 .Lfb0_spin
